# projection epilogue stores back to plain/nt: U-column tiles come only from the static pass; queue-resident K/V tiles publish with one L2 write-back per workgroup when it leaves tile mode (aggregated c
# speedup vs baseline: 1.0273x; 1.0127x over previous
; DI void phase_inproj(int wv, const Params& p, int layer, char* smc) {
;     ...
;       const bool kk = colbase < cV;
;       const int head = (colbase - (kk ? cK : cV)) >> 6;
; #pragma unroll
;       for (int i = 0; i < 4; ++i) {
;         const long row = (long)tm * 128 + wm * 64 + i * 16 + fr;
;         float* dst;
;         if (row < MP) {
;           long b = row >> 12, tt = row & 4095;
;           dst = p.out + (kk ? oPK : oPV) + ((((long)layer * NB + b) * HC + head) * SEQ + tt) * 64;
;         } else {
;           long r2 = row - MP, b = r2 >> 4, tt = r2 & 15;
;           dst = p.out + (kk ? oSK : oSV) + ((((long)layer * NSB + b) * HC + head) * SSEQ + tt) * 64;
;         }
; #pragma unroll
;         for (int n = 0; n < 4; ++n)
;           *(float4*)(dst + n * 16 + 4 * fq) = float4{acc[i][n][0], acc[i][n][1], acc[i][n][2], acc[i][n][3]};
;       }
.LBB0_168:
	s_or_saveexec_b64 s[0:1], s[0:1]
	v_lshrrev_b64 v[74:75], 9, v[66:67]
	v_and_b32_e32 v75, 0xfff, v75
	v_and_b32_e32 v74, -8, v74
	v_lshl_add_u64 v[74:75], v[74:75], 0, s[4:5]
	v_lshl_add_u64 v[72:73], v[74:75], 0, v[72:73]
	v_lshlrev_b64 v[74:75], 20, v[72:73]
	s_xor_b64 exec, exec, s[0:1]
	s_lshl_b32 s8, s6, 2
	s_add_u32 s8, s56, s8
	s_addc_u32 s9, s57, 0
	v_lshlrev_b32_e32 v76, 8, v70
	v_lshl_add_u64 v[72:73], s[8:9], 0, v[74:75]
	v_and_b32_e32 v76, 0xfcf00, v76
	v_mov_b32_e32 v77, v0
	v_lshl_add_u64 v[76:77], v[72:73], 0, v[76:77]
	s_or_b64 exec, exec, s[0:1]
	v_lshlrev_b32_e32 v72, 2, v132
	v_mov_b32_e32 v73, v0
	v_lshl_add_u64 v[76:77], v[76:77], 0, v[72:73]
	global_store_dwordx4 v[76:77], v[2:5], off
	global_store_dwordx4 v[76:77], v[18:21], off offset:64
	global_store_dwordx4 v[76:77], v[14:17], off offset:128
	global_store_dwordx4 v[76:77], v[10:13], off offset:192
	v_or_b32_e32 v76, 16, v70
	v_mov_b32_e32 v77, v71
	v_cmp_lt_i64_e32 vcc, s[20:21], v[76:77]
	s_and_saveexec_b64 s[0:1], vcc
	s_xor_b64 s[0:1], exec, s[0:1]
	s_cbranch_execz .LBB0_172
	s_mov_b32 s8, 0xffff0000
	s_mov_b32 s9, 0x1fffff
	v_readlane_b32 s16, v255, 11
	s_mov_b32 s8, s16
	v_lshl_add_u64 v[76:77], v[66:67], 0, s[8:9]
	v_lshrrev_b64 v[76:77], 1, v[76:77]
	s_lshl_b32 s8, s7, 2
	s_add_u32 s8, s56, s8
	v_lshl_add_u64 v[76:77], v[68:69], 0, v[76:77]
	v_readlane_b32 s17, v255, 12
	s_addc_u32 s9, s57, 0
	v_lshlrev_b64 v[76:77], 12, v[76:77]
	v_writelane_b32 v255, s16, 11
	v_lshl_add_u64 v[76:77], s[8:9], 0, v[76:77]
	v_lshl_add_u64 v[78:79], v[76:77], 0, v[136:137]
	v_writelane_b32 v255, s17, 12
.LBB0_172:
	s_andn2_saveexec_b64 s[0:1], s[0:1]
	s_lshl_b32 s8, s6, 2
	s_add_u32 s8, s56, s8
	s_addc_u32 s9, s57, 0
	v_lshlrev_b32_e32 v73, 8, v76
	v_lshl_add_u64 v[78:79], s[8:9], 0, v[74:75]
	v_and_b32_e32 v76, 0xfdf00, v73
	v_mov_b32_e32 v77, v0
	v_lshl_add_u64 v[78:79], v[78:79], 0, v[76:77]
	s_or_b64 exec, exec, s[0:1]
	v_mov_b32_e32 v73, v0
	v_lshl_add_u64 v[76:77], v[78:79], 0, v[72:73]
	global_store_dwordx4 v[76:77], v[6:9], off
	global_store_dwordx4 v[76:77], v[22:25], off offset:64
	global_store_dwordx4 v[76:77], v[26:29], off offset:128
	global_store_dwordx4 v[76:77], v[30:33], off offset:192
	v_or_b32_e32 v76, 32, v70
	v_mov_b32_e32 v77, v71
	v_cmp_lt_i64_e32 vcc, s[20:21], v[76:77]
	s_and_saveexec_b64 s[0:1], vcc
	s_xor_b64 s[0:1], exec, s[0:1]
	s_cbranch_execz .LBB0_176
	s_mov_b32 s8, 0xffff0000
	s_mov_b32 s9, 0x1fffff
	v_readlane_b32 s16, v255, 13
	s_mov_b32 s8, s16
	v_lshl_add_u64 v[76:77], v[66:67], 0, s[8:9]
	v_lshrrev_b64 v[76:77], 1, v[76:77]
	s_lshl_b32 s8, s7, 2
	s_add_u32 s8, s56, s8
	v_lshl_add_u64 v[76:77], v[68:69], 0, v[76:77]
	v_readlane_b32 s17, v255, 14
	s_addc_u32 s9, s57, 0
	v_lshlrev_b64 v[76:77], 12, v[76:77]
	v_writelane_b32 v255, s16, 13
	v_lshl_add_u64 v[76:77], s[8:9], 0, v[76:77]
	v_lshl_add_u64 v[78:79], v[76:77], 0, v[136:137]
	v_writelane_b32 v255, s17, 14
.LBB0_176:
	s_andn2_saveexec_b64 s[0:1], s[0:1]
	s_lshl_b32 s8, s6, 2
	s_add_u32 s8, s56, s8
	s_addc_u32 s9, s57, 0
	v_lshlrev_b32_e32 v73, 8, v76
	v_lshl_add_u64 v[78:79], s[8:9], 0, v[74:75]
	v_and_b32_e32 v76, 0xfef00, v73
	v_mov_b32_e32 v77, v0
	v_lshl_add_u64 v[78:79], v[78:79], 0, v[76:77]
	s_or_b64 exec, exec, s[0:1]
	v_mov_b32_e32 v73, v0
	v_or_b32_e32 v70, 48, v70
	v_lshl_add_u64 v[76:77], v[78:79], 0, v[72:73]
	v_cmp_lt_i64_e32 vcc, s[20:21], v[70:71]
	global_store_dwordx4 v[76:77], v[34:37], off
	global_store_dwordx4 v[76:77], v[38:41], off offset:64
	global_store_dwordx4 v[76:77], v[42:45], off offset:128
	global_store_dwordx4 v[76:77], v[46:49], off offset:192
	s_and_saveexec_b64 s[0:1], vcc
	s_xor_b64 s[0:1], exec, s[0:1]
	s_cbranch_execz .LBB0_180
	s_mov_b32 s8, 0xffff0000
	s_mov_b32 s9, 0x1fffff
	v_readlane_b32 s16, v255, 15
	s_mov_b32 s8, s16
	v_lshl_add_u64 v[70:71], v[66:67], 0, s[8:9]
	v_lshrrev_b64 v[70:71], 1, v[70:71]
	s_lshl_b32 s7, s7, 2
	s_add_u32 s8, s56, s7
	v_lshl_add_u64 v[68:69], v[68:69], 0, v[70:71]
	v_readlane_b32 s17, v255, 16
	s_addc_u32 s9, s57, 0
	v_lshlrev_b64 v[68:69], 12, v[68:69]
	v_writelane_b32 v255, s16, 15
	v_lshl_add_u64 v[68:69], s[8:9], 0, v[68:69]
	v_lshl_add_u64 v[76:77], v[68:69], 0, v[136:137]
	v_writelane_b32 v255, s17, 16
; DI unsigned pack2(float a, float b) { f32x2_t v = {a, b}; return __builtin_bit_cast(unsigned, __builtin_convertvector(v, bf16x2_t)); }
; DI void phase_inproj(int wv, const Params& p, int layer, char* smc) {
;     ...
;     if (colbase < NU) {
;       u16* blk = U + (size_t)(colbase >> 6) * MT * 64 + ((size_t)tm * 128 + wm * 64) * 64;
;       u16* R = (u16*)smc + wave * (64 * 72);
; #pragma unroll
;       for (int i = 0; i < 4; ++i)
; #pragma unroll
;         for (int n = 0; n < 4; ++n) {
;           u32x2 pk;
;           pk[0] = pack2(acc[i][n][0], acc[i][n][1]);
;           pk[1] = pack2(acc[i][n][2], acc[i][n][3]);
;           *(u32x2*)(R + (i * 16 + fr) * 72 + n * 16 + 4 * fq) = pk;
;         }
; #pragma unroll
;       for (int k = 0; k < 8; ++k) {
;         const int id = lane + 64 * k, r = id >> 3, c = id & 7;
;         __builtin_nontemporal_store(*(const u32x4*)(R + r * 72 + c * 8), (u32x4*)(blk + r * 64 + c * 8));
;       }
;     ...
; #pragma unroll
;         for (int n = 0; n < 4; ++n)
;           *(float4*)(dst + n * 16 + 4 * fq) = float4{acc[i][n][0], acc[i][n][1], acc[i][n][2], acc[i][n][3]};
.LBB0_180:
	s_andn2_saveexec_b64 s[0:1], s[0:1]
	s_lshl_b32 s6, s6, 2
	s_add_u32 s6, s56, s6
	s_addc_u32 s7, s57, 0
	v_lshlrev_b32_e32 v70, 8, v70
	v_lshl_add_u64 v[68:69], s[6:7], 0, v[74:75]
	v_and_b32_e32 v70, 0xfff00, v70
	v_mov_b32_e32 v71, v0
	v_lshl_add_u64 v[76:77], v[68:69], 0, v[70:71]
	s_or_b64 exec, exec, s[0:1]
	v_mov_b32_e32 v73, v0
	v_lshl_add_u64 v[68:69], v[76:77], 0, v[72:73]
	global_store_dwordx4 v[68:69], v[50:53], off
	global_store_dwordx4 v[68:69], v[54:57], off offset:64
	global_store_dwordx4 v[68:69], v[58:61], off offset:128
	global_store_dwordx4 v[68:69], v[62:65], off offset:192
	s_branch .LBB0_153
.LBB0_183:
	v_cvt_pk_bf16_f32 v2, v2, v3
	v_cvt_pk_bf16_f32 v3, v4, v5
	v_cvt_pk_bf16_f32 v4, v18, v19
	v_cvt_pk_bf16_f32 v5, v20, v21
	ds_write2_b64 v133, v[2:3], v[4:5] offset1:4
	v_cvt_pk_bf16_f32 v2, v14, v15
	v_cvt_pk_bf16_f32 v3, v16, v17
	v_cvt_pk_bf16_f32 v4, v10, v11
	v_cvt_pk_bf16_f32 v5, v12, v13
	ds_write2_b64 v133, v[2:3], v[4:5] offset0:8 offset1:12
	v_cvt_pk_bf16_f32 v2, v6, v7
	v_cvt_pk_bf16_f32 v3, v8, v9
	v_cvt_pk_bf16_f32 v4, v22, v23
	v_cvt_pk_bf16_f32 v5, v24, v25
	v_add_u32_e32 v6, 0x800, v133
	ds_write2_b64 v6, v[2:3], v[4:5] offset0:32 offset1:36
	v_cvt_pk_bf16_f32 v2, v26, v27
	v_cvt_pk_bf16_f32 v3, v28, v29
	v_cvt_pk_bf16_f32 v4, v30, v31
	v_cvt_pk_bf16_f32 v5, v32, v33
	ds_write2_b64 v6, v[2:3], v[4:5] offset0:40 offset1:44
	v_cvt_pk_bf16_f32 v2, v34, v35
	v_cvt_pk_bf16_f32 v3, v36, v37
	v_cvt_pk_bf16_f32 v4, v38, v39
	v_cvt_pk_bf16_f32 v5, v40, v41
	v_add_u32_e32 v6, 0x1000, v133
	ds_write2_b64 v6, v[2:3], v[4:5] offset0:64 offset1:68
	v_cvt_pk_bf16_f32 v2, v42, v43
	v_cvt_pk_bf16_f32 v3, v44, v45
	v_cvt_pk_bf16_f32 v4, v46, v47
	v_cvt_pk_bf16_f32 v5, v48, v49
	v_lshrrev_b32_e32 v68, 6, v80
	s_mov_b32 s0, 0x810000
	ds_write2_b64 v6, v[2:3], v[4:5] offset0:72 offset1:76
	v_cvt_pk_bf16_f32 v2, v50, v51
	v_cvt_pk_bf16_f32 v3, v52, v53
	v_cvt_pk_bf16_f32 v4, v54, v55
	v_cvt_pk_bf16_f32 v5, v56, v57
	v_add_u32_e32 v6, 0x1800, v133
	v_mul_lo_u32 v68, v68, s0
	v_mov_b32_e32 v69, v0
	ds_write2_b64 v6, v[2:3], v[4:5] offset0:96 offset1:100
	v_cvt_pk_bf16_f32 v2, v58, v59
	v_cvt_pk_bf16_f32 v3, v60, v61
	v_cvt_pk_bf16_f32 v4, v62, v63
	v_cvt_pk_bf16_f32 v5, v64, v65
	v_lshlrev_b64 v[66:67], 7, v[66:67]
	ds_write2_b64 v6, v[2:3], v[4:5] offset0:104 offset1:108
	v_lshl_add_u64 v[2:3], s[76:77], 0, v[68:69]
	v_lshl_add_u64 v[6:7], v[2:3], 0, v[66:67]
	v_mov_b32_e32 v141, v0
	ds_read_b128 v[2:5], v162
	v_lshl_add_u64 v[10:11], v[6:7], 0, v[140:141]
	ds_read_b128 v[6:9], v162 offset:1152
	v_mov_b32_e32 v143, v0
	v_lshl_add_u64 v[12:13], v[10:11], 0, v[142:143]
	v_mov_b32_e32 v145, v0
	s_waitcnt lgkmcnt(1)
	global_store_dwordx4 v[12:13], v[2:5], off nt
	v_lshl_add_u64 v[12:13], v[10:11], 0, v[144:145]
	ds_read_b128 v[2:5], v162 offset:2304
	s_waitcnt lgkmcnt(1)
	global_store_dwordx4 v[12:13], v[6:9], off nt
	ds_read_b128 v[6:9], v162 offset:3456
	v_mov_b32_e32 v147, v0
	v_lshl_add_u64 v[12:13], v[10:11], 0, v[146:147]
	v_mov_b32_e32 v149, v0
	s_waitcnt lgkmcnt(1)
	global_store_dwordx4 v[12:13], v[2:5], off nt
	v_lshl_add_u64 v[12:13], v[10:11], 0, v[148:149]
	ds_read_b128 v[2:5], v162 offset:4608
	s_waitcnt lgkmcnt(1)
	global_store_dwordx4 v[12:13], v[6:9], off nt
	ds_read_b128 v[6:9], v162 offset:5760
	v_mov_b32_e32 v151, v0
	v_lshl_add_u64 v[12:13], v[10:11], 0, v[150:151]
	v_mov_b32_e32 v153, v0
	s_waitcnt lgkmcnt(1)
	global_store_dwordx4 v[12:13], v[2:5], off nt
	v_lshl_add_u64 v[12:13], v[10:11], 0, v[152:153]
	ds_read_b128 v[2:5], v162 offset:6912
	s_waitcnt lgkmcnt(1)
	global_store_dwordx4 v[12:13], v[6:9], off nt
	ds_read_b128 v[6:9], v162 offset:8064
	v_mov_b32_e32 v155, v0
	v_lshl_add_u64 v[12:13], v[10:11], 0, v[154:155]
	v_mov_b32_e32 v157, v0
	s_waitcnt lgkmcnt(1)
	global_store_dwordx4 v[12:13], v[2:5], off nt
	s_nop 1
	v_lshl_add_u64 v[2:3], v[10:11], 0, v[156:157]
	s_waitcnt lgkmcnt(0)
	global_store_dwordx4 v[2:3], v[6:9], off nt
	s_branch .LBB0_153

; DI void phase_mixers(int wv, const Params& p, int layer, char* smc, int dryType) {
;     ...
;     int it = s_item;
;     if (it >= NITEMS) break;
;     int type, b = 0, h = 0, qb = 0, cvit = 0; bool samp = false;
;     if (it < IT_RP) { type = 0; b = it / HA; h = it % HA; }
;     else if ((it -= IT_RP) < IT_CV) { type = 3; cvit = it; }
;     else if ((it -= IT_CV) < IT_MP) { type = 1; b = it / HB; h = it % HB; }
;     else if ((it -= IT_MP) < IT_RS) { type = 0; samp = true; b = it / HA; h = it % HA; }
;     else if ((it -= IT_RS) < IT_MS) { type = 1; samp = true; b = it / HB; h = it % HB; }
;     else if ((it -= IT_MS) < IT_SS) { type = 2; samp = true; b = it / HC; h = it % HC; }
;     else { it -= IT_SS; type = 2; qb = it % (SEQ / 64); int bh = it / (SEQ / 64); b = bh / HC; h = bh % HC; }
.LBB0_205:
	s_or_b64 exec, exec, s[0:1]
	s_waitcnt lgkmcnt(0)
	s_barrier
	ds_read_b32 v1, v0 offset:65472
	s_movk_i32 s0, 0x395f
	s_waitcnt lgkmcnt(0)
	v_cmp_lt_i32_e32 vcc, s0, v1
	v_readfirstlane_b32 s3, v1
	s_mov_b64 s[0:1], -1
	s_cbranch_vccnz .LBB0_200
	s_cmpk_lt_u32 s3, 0xc0
	s_cbranch_scc1 .Lq_old
	s_sub_u32 s3, s3, 0xc0
	s_cmpk_lt_u32 s3, 0x1020
	s_cbranch_scc1 .Lq_gemm
	s_sub_u32 s3, s3, 0xf60
	v_readlane_b32 s6, v255, 50
	s_cmp_eq_u32 s6, 0
	s_cbranch_scc1 .Lq_nofl
	s_waitcnt vmcnt(0)
	s_barrier
	s_and_saveexec_b64 s[0:1], s[10:11]
	s_cbranch_execz .Lq_fl1
	v_readlane_b32 s8, v255, 22
	v_readlane_b32 s9, v255, 23
	buffer_wbl2 sc1
	s_waitcnt vmcnt(0)
	v_mov_b32_e32 v1, s6
	s_nop 3
	global_atomic_add v0, v1, s[8:9] offset:8

; DI void phase_mixers(int wv, const Params& p, int layer, char* smc, int dryType) {
;     ...
;     int it = s_item;
;     if (it >= NITEMS) break;
.LBB0_838:
	v_readlane_b32 s6, v255, 50
	s_cmp_eq_u32 s6, 0
	s_cbranch_scc1 .Lq_nofl2
	s_waitcnt vmcnt(0)
	s_barrier
	v_readlane_b32 s10, v255, 44
	v_readlane_b32 s11, v255, 45
	s_and_saveexec_b64 s[0:1], s[10:11]
	s_cbranch_execz .Lq_fl2
	v_readlane_b32 s8, v255, 22
	v_readlane_b32 s9, v255, 23
	buffer_wbl2 sc1
	s_waitcnt vmcnt(0)
	v_mov_b32_e32 v1, s6
	s_nop 3
	global_atomic_add v0, v1, s[8:9] offset:8
